# v28 + one static s_setprio 1 for waves 0-3 at kernel entry, all per-segment s_setprio flips deleted (other half of the A/B)
# speedup vs baseline: 1.0029x; 1.0029x over previous
_Z4mega4Args:
	v_readfirstlane_b32 s98, v0
	s_nop 3
	s_and_b32 s98, s98, 0x3ff
	s_lshr_b32 s98, s98, 6
	s_cmp_lt_u32 s98, 4
	s_cbranch_scc0 .Lprio_done
	s_setprio 1
